# prompt chunk loop: 2-deep operand prefetch (two staging register sets by chunk parity, exact counted waits)
# baseline (speedup 1.0000x reference)
.LBB0_2534:
	s_or_b64 exec, exec, s[6:7]
	s_and_b32 s35, s2, 63
	s_add_u32 s6, s64, s4
	s_addc_u32 s7, s65, 0
	v_mov_b32_e32 v2, 0
	v_mov_b32_e32 v97, v2
	s_add_u32 s5, s14, s4
	v_lshl_add_u64 v[98:99], s[6:7], 0, v[96:97]
	s_addc_u32 s12, s15, 0
	s_lshl_b64 s[6:7], s[8:9], 1
	s_add_u32 s6, s5, s6
	s_addc_u32 s7, s12, s7
	s_add_u32 s12, s6, s10
	s_addc_u32 s13, s7, 0
	v_lshlrev_b32_e32 v5, 4, v14
	v_lshlrev_b32_e32 v14, 1, v95
	v_mov_b32_e32 v15, v2
	s_add_u32 s4, s20, s4
	v_lshl_add_u64 v[100:101], s[12:13], 0, v[14:15]
	s_addc_u32 s5, s21, 0
	s_add_i32 s18, 0, 0x11400
	s_lshl_b32 s12, s38, 5
	s_add_u32 s12, s28, s12
	s_addc_u32 s13, s29, 0
	v_mov_b32_e32 v11, v2
	s_add_u32 s12, s12, 0xf191400
	v_or_b32_e32 v16, s16, v1
	v_or_b32_e32 v17, s16, v95
	v_lshl_add_u64 v[102:103], s[4:5], 0, v[10:11]
	v_lshlrev_b32_e32 v10, 4, v13
	s_addc_u32 s13, s13, 0
	v_lshl_add_u64 v[104:105], s[6:7], 0, v[14:15]
	s_add_i32 s6, 0, 0x15c00
	s_movk_i32 s7, 0x90
	v_add_u32_e32 v18, s18, v10
	v_add_u32_e32 v14, s6, v10
	v_mul_lo_u32 v10, v17, s7
	v_lshlrev_b32_e32 v11, 1, v117
	v_mul_lo_u32 v125, v16, s7
	s_movk_i32 s7, 0x48
	v_add3_u32 v123, 0, v10, v11
	v_mul_lo_u32 v10, v17, s7
	v_add_lshl_u32 v10, v10, v117, 1
	v_add_u32_e32 v11, 0x90, v10
	v_add_u32_e32 v128, s18, v11
	v_add_u32_e32 v129, s6, v11
	v_add_u32_e32 v11, 0x120, v10
	v_add_u32_e32 v130, s18, v11
	v_add_u32_e32 v131, s6, v11
	v_add_u32_e32 v11, 0x1b0, v10
	v_add_u32_e32 v132, s18, v11
	v_add_u32_e32 v133, s6, v11
	v_add_u32_e32 v11, 0x900, v10
	v_add_u32_e32 v134, s18, v11
	v_add_u32_e32 v135, s6, v11
	v_add_u32_e32 v11, 0x990, v10
	v_add_u32_e32 v126, s18, v10
	v_add_u32_e32 v127, s6, v10
	v_add_u32_e32 v136, s18, v11
	v_add_u32_e32 v137, s6, v11
	v_add_u32_e32 v11, 0xa20, v10
	v_add_u32_e32 v10, 0xab0, v10
	v_add_u32_e32 v139, s6, v11
	v_add_u32_e32 v141, s6, v10
	s_add_i32 s6, s16, s8
	s_ashr_i32 s16, s6, 4
	s_add_i32 s6, s6, 16
	s_add_i32 s44, s44, s38
	v_add_u32_e32 v138, s18, v11
	v_add_u32_e32 v140, s18, v10
	s_ashr_i32 s18, s6, 4
	s_lshl_b32 s6, s44, 14
	s_mul_i32 s40, s40, 0x8400
	s_add_i32 s38, s6, 0x20000
	s_or_b32 s6, s41, s40
	v_add_lshl_u32 v10, s6, v116, 2
	v_mov_b32_e32 v11, v2
	s_movk_i32 s17, 0x110
	v_lshl_add_u64 v[10:11], s[28:29], 0, v[10:11]
	s_mov_b64 s[6:7], 0xf006400
	s_lshr_b32 s45, s44, 3
	v_or_b32_e32 v119, 32, v94
	s_mov_b32 s11, 0
	v_lshl_add_u32 v122, v94, 1, 0
	v_mul_lo_u32 v15, v16, s17
	v_mul_u32_u24_e32 v16, 0x90, v1
	v_lshl_add_u64 v[106:107], v[10:11], 0, s[6:7]
	s_lshl_b32 s6, s45, 6
	v_add_u32_e32 v148, v12, v4
	v_mbcnt_lo_u32_b32 v4, -1, 0
	v_mul_u32_u24_e32 v120, 0x110, v118
	v_mul_u32_u24_e32 v121, 0x110, v117
	v_cmp_eq_u32_e64 s[4:5], 0, v13
	v_add_u32_e32 v124, 0x900, v123
	s_ashr_i32 s17, s16, 31
	s_ashr_i32 s19, s18, 31
	v_mul_u32_u24_e32 v142, 0x880, v13
	v_mul_u32_u24_e32 v143, 0x110, v119
	s_mov_b32 s39, s11
	s_sub_i32 s46, s6, 64
	s_sub_i32 s47, 0, s45
	v_lshlrev_b32_e32 v144, 1, v5
	v_add_u32_e32 v145, v122, v15
	v_add_u32_e32 v146, v18, v125
	s_mov_b32 s48, 0x5040100
	v_add_u32_e32 v147, v14, v16
	s_mov_b64 s[40:41], 0x1000
	v_mbcnt_hi_u32_b32 v149, -1, v4
	s_mov_b32 s49, s44
	s_mov_b32 s50, s11
	s_mov_b32 s51, s11
	v_mov_b32_e32 v22, 0
	v_mov_b32_e32 v23, v2
	v_mov_b32_e32 v24, v2
	v_mov_b32_e32 v25, v2
	v_mov_b32_e32 v18, 0
	v_mov_b32_e32 v19, v2
	v_mov_b32_e32 v20, v2
	v_mov_b32_e32 v21, v2
	v_mov_b32_e32 v14, 0
	v_mov_b32_e32 v15, v2
	v_mov_b32_e32 v16, v2
	v_mov_b32_e32 v17, v2
	v_mov_b32_e32 v10, 0
	v_mov_b32_e32 v11, v2
	v_mov_b32_e32 v12, v2
	v_mov_b32_e32 v13, v2
	v_and_b32_e32 v222, 7, v116
	v_lshlrev_b32_e32 v223, 4, v222
	v_lshlrev_b32_e32 v225, 5, v222
	v_add_u32_e32 v204, v120, v225
	v_add_u32_e32 v205, v121, v96
	v_mul_u32_u24_e32 v216, 0x90, v118
	v_add_u32_e32 v216, v216, v223
	v_add_u32_e32 v217, 0x13800, v216
	v_add_u32_e32 v218, 0x18000, v216
	v_mul_u32_u24_e32 v219, 0x90, v117
	v_add_u32_e32 v221, v219, v94
	v_add_u32_e32 v221, s10, v221
	v_add_u32_e32 v221, 0x18000, v221
	v_add_u32_e32 v219, v219, v96
	v_add_u32_e32 v220, 0x13800, v219
	s_and_b32 s66, s2, 7
	s_bfe_u32 s67, s2, 0x30003
	s_lshl_b32 s68, s66, 8
	s_and_b32 s69, s2, 64
	s_lshl_b32 s69, s69, 1
	v_lshlrev_b32_e32 v224, 11, v118
	v_add_u32_e32 v224, s68, v224
	v_mov_b32_e32 v227, 0
	v_mov_b32_e32 v229, 0
	v_add_u32_e32 v226, v224, v225
	v_add_u32_e32 v228, v224, v223
	v_add_u32_e32 v228, s69, v228
	s_lshl_b32 s70, s67, 4
	s_add_i32 s70, s70, 0x4400
	s_lshl_b32 s70, s70, 11
	s_add_u32 s36, s20, s70
	s_addc_u32 s37, s21, 0
	v_lshl_add_u64 v[206:207], s[36:37], 0, v[226:227]
	s_add_u32 s36, s64, s70
	s_addc_u32 s37, s65, 0
	v_lshl_add_u64 v[208:209], s[36:37], 0, v[226:227]
	s_add_u32 s36, s14, s70
	s_addc_u32 s37, s15, 0
	v_lshl_add_u64 v[210:211], s[36:37], 0, v[228:229]
	s_mul_i32 s70, s67, 0x108
	s_add_i32 s70, s70, s66
	s_lshl_b32 s71, s70, 14
	s_add_u32 s36, s62, s71
	s_addc_u32 s37, s63, 0
	v_lshlrev_b32_e32 v230, 4, v116
	v_mov_b32_e32 v231, 0
	v_lshl_add_u64 v[212:213], s[36:37], 0, v[230:231]
	v_add_u32_e32 v230, 0x2000, v230
	v_lshl_add_u64 v[214:215], s[36:37], 0, v[230:231]
	v_mov_b32_e32 v38, 0
	v_mov_b32_e32 v39, 0
	v_mov_b64_e32 v[40:41], v[38:39]
	v_mov_b64_e32 v[42:43], v[38:39]
	v_mov_b64_e32 v[44:45], v[38:39]
	v_mov_b64_e32 v[62:63], v[38:39]
	v_mov_b64_e32 v[64:65], v[38:39]
	v_mov_b64_e32 v[66:67], v[38:39]
	v_mov_b64_e32 v[68:69], v[38:39]
	v_mov_b64_e32 v[78:79], v[38:39]
	v_mov_b64_e32 v[80:81], v[38:39]
	v_cmp_gt_u32_e32 vcc, 16, v118
	s_and_saveexec_b64 s[70:71], vcc
	global_load_dwordx4 v[42:45], v[206:207], off
	global_load_dwordx4 v[38:41], v[206:207], off offset:16
	global_load_dwordx4 v[62:65], v[208:209], off
	global_load_dwordx4 v[66:69], v[208:209], off offset:16
	global_load_dwordx4 v[78:81], v[210:211], off nt
	s_or_b64 exec, exec, s[70:71]
	global_load_dwordx4 v[70:73], v[212:213], off
	global_load_dwordx4 v[74:77], v[214:215], off
	s_lshl_b32 s70, s67, 22
	s_add_u32 s36, s20, s70
	s_addc_u32 s37, s21, 0
	v_lshl_add_u64 v[206:207], s[36:37], 0, v[226:227]
	s_add_u32 s36, s64, s70
	s_addc_u32 s37, s65, 0
	v_lshl_add_u64 v[208:209], s[36:37], 0, v[226:227]
	s_add_u32 s36, s14, s70
	s_addc_u32 s37, s15, 0
	v_lshl_add_u64 v[210:211], s[36:37], 0, v[228:229]
	s_mov_b32 s36, 0x20000
	s_mov_b32 s37, 0
	v_lshl_add_u64 v[212:213], v[212:213], 0, s[36:37]
	v_lshl_add_u64 v[214:215], v[214:215], 0, s[36:37]
	global_load_dwordx4 v[82:85], v[206:207], off
	global_load_dwordx4 v[86:89], v[206:207], off offset:16
	global_load_dwordx4 v[90:93], v[208:209], off
	global_load_dwordx4 v[112:115], v[208:209], off offset:16
	global_load_dwordx4 v[232:235], v[210:211], off nt
	global_load_dwordx4 v[224:227], v[212:213], off
	global_load_dwordx4 v[228:231], v[214:215], off
	s_and_saveexec_b64 s[70:71], s[0:1]
	global_load_dword v236, v[106:107], off
	s_or_b64 exec, exec, s[70:71]
	v_lshl_add_u64 v[206:207], v[206:207], 0, s[36:37]
	v_lshl_add_u64 v[208:209], v[208:209], 0, s[36:37]
	v_lshl_add_u64 v[210:211], v[210:211], 0, s[36:37]
	v_lshl_add_u64 v[212:213], v[212:213], 0, s[36:37]
	v_lshl_add_u64 v[214:215], v[214:215], 0, s[36:37]
	v_lshl_add_u64 v[106:107], v[106:107], 0, s[40:41]
	s_waitcnt vmcnt(8)
	s_branch .LBB0_2537

.LBB0_2540:
	s_and_b32 s6, s51, 1
	s_mul_i32 s7, s6, 0x12000
	s_mulk_i32 s6, 0x4800
	s_add_i32 s55, s6, 0
	s_add_i32 s52, s7, 0
	s_add_i32 s55, s55, 0x1a400
	v_add3_u32 v4, s52, v120, v144
	v_lshl_add_u32 v5, v116, 2, s55
	s_cmp_eq_u32 s51, 1
	s_cbranch_scc1 .Lpc_w12
	s_cmp_eq_u32 s51, 32
	s_cbranch_scc1 .Lpc_w8
	s_waitcnt vmcnt(16)
	s_branch .Lpc_wd
.Lpc_w12:
	s_waitcnt vmcnt(12)
	s_branch .Lpc_wd
.Lpc_w8:
	s_waitcnt vmcnt(8)
.Lpc_wd:
	s_bitcmp1_b32 s51, 0
	s_cbranch_scc1 .Lpc_todd
	ds_write_b128 v4, v[42:45] offset:34816
	ds_write_b128 v4, v[38:41] offset:34832
	ds_write_b128 v204, v[62:65] offset:17408
	ds_write_b128 v204, v[66:69] offset:17424
	ds_write_b128 v216, v[70:73] offset:61440
	ds_write_b128 v217, v[74:77]
	ds_write_b128 v218, v[78:81]
	s_and_saveexec_b64 s[6:7], s[0:1]
	ds_write_b32 v5, v3
	s_or_b64 exec, exec, s[6:7]
	s_branch .Lpc_tjoin
.Lpc_todd:
	ds_write_b128 v4, v[82:85] offset:34816
	ds_write_b128 v4, v[86:89] offset:34832
	ds_write_b128 v204, v[90:93] offset:17408
	ds_write_b128 v204, v[112:115] offset:17424
	ds_write_b128 v216, v[224:227] offset:61440
	ds_write_b128 v217, v[228:231]
	ds_write_b128 v218, v[232:235]
	s_and_saveexec_b64 s[6:7], s[0:1]
	ds_write_b32 v5, v236
	s_or_b64 exec, exec, s[6:7]
.Lpc_tjoin:
	s_cmpk_ge_i32 s50, 0xf8
	s_waitcnt lgkmcnt(0)
	s_barrier
	s_cbranch_scc1 .LBB0_2572
	s_bitcmp1_b32 s51, 0
	s_cbranch_scc1 .Lpc_podd
	global_load_dwordx4 v[42:45], v[206:207], off
	global_load_dwordx4 v[38:41], v[206:207], off offset:16
	global_load_dwordx4 v[62:65], v[208:209], off
	global_load_dwordx4 v[66:69], v[208:209], off offset:16
	global_load_dwordx4 v[78:81], v[210:211], off nt
	global_load_dwordx4 v[70:73], v[212:213], off
	global_load_dwordx4 v[74:77], v[214:215], off
	s_and_saveexec_b64 s[6:7], s[0:1]
	global_load_dword v3, v[106:107], off
	s_or_b64 exec, exec, s[6:7]
	s_branch .Lpc_pjoin
.Lpc_podd:
	global_load_dwordx4 v[82:85], v[206:207], off
	global_load_dwordx4 v[86:89], v[206:207], off offset:16
	global_load_dwordx4 v[90:93], v[208:209], off
	global_load_dwordx4 v[112:115], v[208:209], off offset:16
	global_load_dwordx4 v[232:235], v[210:211], off nt
	global_load_dwordx4 v[224:227], v[212:213], off
	global_load_dwordx4 v[228:231], v[214:215], off
	s_and_saveexec_b64 s[6:7], s[0:1]
	global_load_dword v236, v[106:107], off
	s_or_b64 exec, exec, s[6:7]
.Lpc_pjoin:
	v_lshl_add_u64 v[206:207], v[206:207], 0, s[36:37]
	v_lshl_add_u64 v[208:209], v[208:209], 0, s[36:37]
	v_lshl_add_u64 v[210:211], v[210:211], 0, s[36:37]
	v_lshl_add_u64 v[212:213], v[212:213], 0, s[36:37]
	v_lshl_add_u64 v[214:215], v[214:215], 0, s[36:37]
